# moba_attn unit search: after the first unit search only [cur, cur+2) of the unit prefix (one LDS round trip instead of eight)
# speedup vs baseline: 1.0057x; 1.0006x over previous
.LBB0_1249:
	s_mov_b32 s1, s17
	s_movk_i32 s2, 0x100
	s_mov_b32 s0, 0
	s_cmp_lt_i32 s17, 0
	s_cbranch_scc1 .Lattn_bsfull
	s_mov_b32 s0, s17
	s_add_i32 s2, s17, 2
.Lattn_bsfull:
.LBB0_1250:
	s_add_i32 s3, s2, s0
	s_ashr_i32 s3, s3, 1
	s_lshl_b32 s4, s3, 2
	s_add_i32 s4, s4, 0
	v_mov_b32_e32 v2, s4
	ds_read_b32 v2, v2
	s_waitcnt lgkmcnt(0)
	v_readfirstlane_b32 s4, v2
	s_cmp_gt_i32 s4, s38
	s_cselect_b32 s2, s3, s2
	s_cselect_b32 s0, s0, s3
	s_sub_i32 s3, s2, s0
	s_cmp_gt_i32 s3, 1
	s_cbranch_scc1 .LBB0_1250
	s_lshl_b32 s2, s0, 2
	s_add_i32 s2, s2, 0
	v_mov_b32_e32 v2, s2
	ds_read_b32 v2, v2
	s_ashr_i32 s36, s0, 4
	s_and_b32 s18, s0, 15
	s_ashr_i32 s31, s0, 7
	s_and_b32 s30, s36, 7
	s_waitcnt lgkmcnt(0)
	v_readfirstlane_b32 s4, v2
	s_cmp_lg_u32 s0, s1
	s_mov_b64 s[2:3], -1
	s_cbranch_scc0 .LBB0_1253
	s_lshl_b32 s2, s31, 12
	s_lshl_b32 s19, s18, 8
	s_or_b32 s3, s2, s19
	v_add_u32_e32 v4, s3, v141
	v_mov_b64_e32 v[2:3], s[92:93]
	v_mad_i64_i32 v[2:3], s[6:7], v4, s63, v[2:3]
	s_lshl_b32 s24, s30, 8
	v_lshl_add_u64 v[2:3], v[2:3], 0, s[24:25]
	s_waitcnt vmcnt(5)
	v_mov_b32_e32 v143, v1
	s_waitcnt vmcnt(1)
	v_lshl_add_u64 v[58:59], v[2:3], 0, v[142:143]
	v_lshl_add_u32 v2, s30, 7, v152
	v_ashrrev_i32_e32 v3, 31, v2
	v_lshlrev_b64 v[2:3], 14, v[2:3]
	v_lshl_add_u64 v[2:3], s[34:35], 0, v[2:3]
	s_ashr_i32 s3, s2, 31
	v_lshl_add_u64 v[2:3], s[2:3], 1, v[2:3]
	s_lshl_b32 s24, s18, 9
	v_lshl_add_u64 v[2:3], v[2:3], 0, s[24:25]
	v_mov_b32_e32 v145, v1
	s_mov_b32 s2, 0x19ca1000
	s_waitcnt vmcnt(0)
	v_lshl_add_u64 v[60:61], v[2:3], 0, v[144:145]
	v_add_co_u32_e32 v2, vcc, s2, v58
	s_mov_b32 s2, 0x19d41000
	s_nop 0
	v_addc_co_u32_e32 v3, vcc, 0, v59, vcc
	v_add_co_u32_e32 v10, vcc, s2, v58
	s_mov_b32 s2, 0x40000
	s_nop 0
	v_addc_co_u32_e32 v11, vcc, 0, v59, vcc
	v_add_co_u32_e32 v14, vcc, s2, v60
	s_mov_b32 s2, 0x19de1000
	s_nop 0
	v_addc_co_u32_e32 v15, vcc, 0, v61, vcc
	v_add_co_u32_e32 v18, vcc, s2, v58
	s_mov_b32 s2, 0x80000
	s_nop 0
	v_addc_co_u32_e32 v19, vcc, 0, v59, vcc
	v_add_co_u32_e32 v22, vcc, s2, v60
	s_mov_b32 s2, 0x19e81000
	s_nop 0
	v_addc_co_u32_e32 v23, vcc, 0, v61, vcc
	v_add_co_u32_e32 v26, vcc, s2, v58
	s_mov_b32 s2, 0xc0000
	s_nop 0
	v_addc_co_u32_e32 v27, vcc, 0, v59, vcc
	v_add_co_u32_e32 v30, vcc, s2, v60
	s_mov_b32 s2, 0x19f21000
	s_nop 0
	v_addc_co_u32_e32 v31, vcc, 0, v61, vcc
	v_add_co_u32_e32 v34, vcc, s2, v58
	s_mov_b32 s2, 0x100000
	s_nop 0
	v_addc_co_u32_e32 v35, vcc, 0, v59, vcc
	v_add_co_u32_e32 v38, vcc, s2, v60
	s_mov_b32 s2, 0x19fc1000
	s_nop 0
	v_addc_co_u32_e32 v39, vcc, 0, v61, vcc
	v_add_co_u32_e32 v42, vcc, s2, v58
	s_mov_b32 s2, 0x140000
	s_nop 0
	v_addc_co_u32_e32 v43, vcc, 0, v59, vcc
	v_add_co_u32_e32 v46, vcc, s2, v60
	s_mov_b32 s2, 0x1a061000
	s_nop 0
	v_addc_co_u32_e32 v47, vcc, 0, v61, vcc
	v_add_co_u32_e32 v50, vcc, s2, v58
	s_mov_b32 s2, 0x180000
	s_nop 0
	v_addc_co_u32_e32 v51, vcc, 0, v59, vcc
	v_add_co_u32_e32 v54, vcc, s2, v60
	s_mov_b32 s2, 0x1a101000
	s_nop 0
	v_addc_co_u32_e32 v55, vcc, 0, v61, vcc
	v_add_co_u32_e32 v58, vcc, s2, v58
	s_mov_b32 s2, 0x1c0000
	s_nop 0
	v_addc_co_u32_e32 v59, vcc, 0, v59, vcc
	v_add_co_u32_e32 v62, vcc, s2, v60
	s_nop 1
	v_addc_co_u32_e32 v63, vcc, 0, v61, vcc
	s_barrier
	global_load_dwordx4 v[2:5], v[2:3], off offset:1024
	s_nop 0
	global_load_dwordx4 v[6:9], v[60:61], off
	s_nop 0
	global_load_dwordx4 v[10:13], v[10:11], off offset:1024
	s_nop 0
	global_load_dwordx4 v[14:17], v[14:15], off
	s_nop 0
	global_load_dwordx4 v[18:21], v[18:19], off offset:1024
	s_nop 0
	global_load_dwordx4 v[22:25], v[22:23], off
	s_nop 0
	global_load_dwordx4 v[26:29], v[26:27], off offset:1024
	s_nop 0
	global_load_dwordx4 v[30:33], v[30:31], off
	s_nop 0
	global_load_dwordx4 v[34:37], v[34:35], off offset:1024
	s_nop 0
	global_load_dwordx4 v[38:41], v[38:39], off
	s_nop 0
	global_load_dwordx4 v[42:45], v[42:43], off offset:1024
	s_nop 0
	global_load_dwordx4 v[46:49], v[46:47], off
	s_nop 0
	global_load_dwordx4 v[50:53], v[50:51], off offset:1024
	s_nop 0
	global_load_dwordx4 v[54:57], v[54:55], off
	s_nop 0
	global_load_dwordx4 v[58:61], v[58:59], off offset:1024
	s_nop 0
	global_load_dwordx4 v[62:65], v[62:63], off
	s_mov_b64 s[2:3], 0
	s_waitcnt vmcnt(15)
	ds_write_b128 v157, v[2:5] offset:2048
	s_waitcnt vmcnt(14)
	ds_write_b128 v158, v[6:9]
	s_waitcnt vmcnt(13)
	ds_write_b128 v157, v[10:13] offset:10752
	s_waitcnt vmcnt(12)
	ds_write_b128 v158, v[14:17] offset:8448
	s_waitcnt vmcnt(11)
	ds_write_b128 v157, v[18:21] offset:19456
	s_waitcnt vmcnt(10)
	ds_write_b128 v158, v[22:25] offset:16896
	s_waitcnt vmcnt(9)
	ds_write_b128 v157, v[26:29] offset:28160
	s_waitcnt vmcnt(8)
	ds_write_b128 v158, v[30:33] offset:25344
	s_waitcnt vmcnt(7)
	ds_write_b128 v157, v[34:37] offset:36864
	s_waitcnt vmcnt(6)
	ds_write_b128 v158, v[38:41] offset:33792
	s_waitcnt vmcnt(5)
	ds_write_b128 v157, v[42:45] offset:45568
	s_waitcnt vmcnt(4)
	ds_write_b128 v158, v[46:49] offset:42240
	s_waitcnt vmcnt(3)
	ds_write_b128 v157, v[50:53] offset:54272
	s_waitcnt vmcnt(2)
	ds_write_b128 v158, v[54:57] offset:50688
	s_waitcnt vmcnt(1)
	ds_write_b128 v157, v[58:61] offset:62976
	s_waitcnt vmcnt(0)
	ds_write_b128 v158, v[62:65] offset:59136
	s_waitcnt lgkmcnt(0)
	s_barrier
